# v3 + attention softmax: removed NaN-canonicalising v_max pairs (scores never NaN), max taken directly on score pairs
# speedup vs baseline: 1.0096x; 1.0048x over previous
.LBB0_37:
	s_cmp_eq_u32 s47, 1
	s_movk_i32 s29, 0x400
	s_cselect_b32 s29, 0x100, s29
	s_cmp_lg_u32 s47, 0
	s_cselect_b32 s34, s29, 64
	s_sub_i32 s29, s70, s34
	s_max_i32 s92, s29, 0
	s_lshl_b32 s29, s47, 2
	s_add_i32 s29, s29, s68
	s_lshl_b32 s30, s29, 7
	s_ashr_i32 s31, s30, 31
	v_lshl_add_u64 v[66:67], s[30:31], 1, v[148:149]
	v_mov_b32_e32 v0, v223
	global_load_dwordx4 v[98:101], v[66:67], off
	global_load_dwordx4 v[102:105], v[66:67], off offset:32
	global_load_dwordx4 v[106:109], v[66:67], off offset:64
	global_load_dwordx4 v[110:113], v[66:67], off offset:96
	global_load_dwordx4 v[114:117], v[66:67], off offset:128
	global_load_dwordx4 v[118:121], v[66:67], off offset:160
	global_load_dwordx4 v[122:125], v[66:67], off offset:192
	global_load_dwordx4 v[126:129], v[66:67], off offset:224
	v_ashrrev_i32_e32 v66, 31, v0
	v_lshrrev_b32_e32 v66, 28, v66
	v_add_u32_e32 v66, v0, v66
	v_ashrrev_i32_e32 v86, 4, v66
	v_and_b32_e32 v66, -16, v66
	v_add_u32_e32 v71, 0x200, v0
	v_sub_u32_e32 v70, v0, v66
	v_ashrrev_i32_e32 v66, 31, v71
	v_lshrrev_b32_e32 v66, 28, v66
	v_add_u32_e32 v66, v71, v66
	v_ashrrev_i32_e32 v87, 4, v66
	v_and_b32_e32 v66, -16, v66
	v_sub_u32_e32 v72, v71, v66
	v_add_u32_e32 v68, s92, v86
	v_mov_b64_e32 v[66:67], s[26:27]
	v_lshlrev_b32_e32 v82, 3, v70
	v_mad_i64_i32 v[68:69], s[30:31], v68, s84, v[66:67]
	v_ashrrev_i32_e32 v83, 31, v82
	v_lshl_add_u64 v[68:69], v[82:83], 1, v[68:69]
	global_load_dwordx4 v[130:133], v[68:69], off
	v_add_u32_e32 v68, s92, v87
	v_lshlrev_b32_e32 v84, 3, v72
	v_mad_i64_i32 v[66:67], s[30:31], v68, s84, v[66:67]
	v_ashrrev_i32_e32 v85, 31, v84
	v_lshl_add_u64 v[66:67], v[84:85], 1, v[66:67]
	s_lshl_b32 s29, s92, 1
	global_load_dwordx4 v[134:137], v[66:67], off
	s_add_u32 s30, s43, s29
	v_lshlrev_b32_e32 v66, 4, v0
	s_addc_u32 s31, s44, 0
	v_and_b32_e32 v152, 0x70, v66
	v_mov_b32_e32 v153, v1
	v_lshl_add_u64 v[66:67], s[30:31], 0, v[152:153]
	v_ashrrev_i32_e32 v88, 3, v0
	v_ashrrev_i32_e32 v89, 3, v71
	v_mad_i64_i32 v[68:69], s[30:31], v88, s85, v[66:67]
	v_mad_i64_i32 v[66:67], s[30:31], v89, s85, v[66:67]
	global_load_dwordx4 v[138:141], v[68:69], off
	global_load_dwordx4 v[142:145], v[66:67], off
	s_movk_i32 s29, 0x110
	v_mul_lo_u32 v153, v86, s29
	v_lshlrev_b32_e32 v170, 4, v70
	v_add3_u32 v66, 0, v153, v170
	v_mul_lo_u32 v171, v87, s29
	v_lshlrev_b32_e32 v172, 4, v72
	s_movk_i32 s29, 0x90
	v_mul_lo_u32 v173, v88, s29
	v_mul_lo_u32 v174, v89, s29
	s_mov_b32 s29, 0xfe967699
	v_cmp_gt_f32_e32 vcc, s29, v169
	s_waitcnt vmcnt(3)
	ds_write_b128 v66, v[130:133]
	v_add3_u32 v66, 0, v171, v172
	s_waitcnt vmcnt(2)
	ds_write_b128 v66, v[134:137]
	v_add_u32_e32 v66, 0, v152
	v_add_u32_e32 v67, v66, v173
	v_add_u32_e32 v66, v66, v174
	s_waitcnt vmcnt(1)
	ds_write_b128 v67, v[138:141] offset:17408
	s_waitcnt vmcnt(0)
	ds_write_b128 v66, v[142:145] offset:17408
	s_waitcnt lgkmcnt(0)
	s_barrier
	s_and_saveexec_b64 s[30:31], vcc
	s_cbranch_execz .LBB0_39
	v_add_u32_e32 v94, 0, v166
	ds_read_b128 v[66:69], v94
	ds_read_b128 v[90:93], v94 offset:32
	s_mov_b32 s29, 0xc2700000
	s_waitcnt lgkmcnt(1)
	v_mfma_f32_32x32x16_bf16 v[66:81], v[66:69], v[98:101], 0
	s_waitcnt lgkmcnt(0)
	v_mfma_f32_32x32x16_bf16 v[66:81], v[90:93], v[102:105], v[66:81]
	ds_read_b128 v[90:93], v94 offset:64
	s_waitcnt lgkmcnt(0)
	v_mfma_f32_32x32x16_bf16 v[66:81], v[90:93], v[106:109], v[66:81]
	ds_read_b128 v[90:93], v94 offset:96
	s_waitcnt lgkmcnt(0)
	v_mfma_f32_32x32x16_bf16 v[66:81], v[90:93], v[110:113], v[66:81]
	ds_read_b128 v[90:93], v94 offset:128
	s_waitcnt lgkmcnt(0)
	v_mfma_f32_32x32x16_bf16 v[66:81], v[90:93], v[114:117], v[66:81]
	ds_read_b128 v[90:93], v94 offset:160
	s_waitcnt lgkmcnt(0)
	v_mfma_f32_32x32x16_bf16 v[66:81], v[90:93], v[118:121], v[66:81]
	ds_read_b128 v[90:93], v94 offset:192
	s_waitcnt lgkmcnt(0)
	v_mfma_f32_32x32x16_bf16 v[66:81], v[90:93], v[122:125], v[66:81]
	ds_read_b128 v[90:93], v94 offset:224
	s_waitcnt lgkmcnt(0)
	v_mfma_f32_32x32x16_bf16 v[66:81], v[90:93], v[126:129], v[66:81]
	v_and_b32_e32 v91, 64, v210
	v_xor_b32_e32 v90, 32, v210
	v_add_u32_e32 v91, 64, v91
	v_cmp_lt_i32_e32 vcc, v90, v91
	s_nop 7
	v_max_f32_e32 v66, v66, v67
	v_max3_f32 v66, v66, v68, v69
	v_max3_f32 v66, v66, v70, v71
	v_max3_f32 v66, v66, v72, v73
	v_max3_f32 v66, v66, v74, v75
	v_max3_f32 v66, v66, v76, v77
	v_cndmask_b32_e32 v90, v210, v90, vcc
	v_max3_f32 v66, v66, v78, v79
	v_max3_f32 v66, v66, v80, v81
	v_lshlrev_b32_e32 v67, 2, v90
	ds_bpermute_b32 v67, v67, v66
	s_waitcnt lgkmcnt(0)
	v_max3_f32 v169, v66, v67, s29

.LBB0_64:
	s_and_b64 vcc, exec, s[0:1]
	s_cbranch_vccz .LBB0_74
	s_add_i32 s0, s70, s59
	s_ashr_i32 s1, s0, 31
	v_mov_b32_e32 v8, v222
	s_add_u32 s0, s0, s24
	v_readlane_b32 s26, v251, 57
	s_addc_u32 s1, s1, s25
	v_and_b32_e32 v0, 31, v8
	v_readlane_b32 s27, v251, 58
	s_waitcnt vmcnt(0)
	v_lshl_add_u64 v[146:147], s[0:1], 0, v[0:1]
	v_ashrrev_i32_e32 v158, 5, v8
	v_mov_b64_e32 v[2:3], s[26:27]
	v_mad_u64_u32 v[2:3], s[0:1], v146, s84, v[2:3]
	s_lshl_b32 s0, s68, 7
	v_mad_i32_i24 v3, v147, s84, v3
	s_ashr_i32 s1, s0, 31
	v_lshlrev_b32_e32 v4, 3, v158
	v_lshl_add_u64 v[2:3], s[0:1], 1, v[2:3]
	v_ashrrev_i32_e32 v5, 31, v4
	v_lshl_add_u64 v[2:3], v[4:5], 1, v[2:3]
	s_mov_b64 s[28:29], 0x1000
	s_movk_i32 s40, 0x1000
	v_lshl_add_u64 v[4:5], v[2:3], 0, s[28:29]
	s_mul_i32 s74, s24, 0x2800
	v_add_co_u32_e32 v2, vcc, s40, v2
	s_mul_hi_i32 s73, s24, 0x2800
	s_add_u32 s30, s26, s74
	v_mov_b32_e32 v38, v223
	v_addc_co_u32_e32 v3, vcc, 0, v3, vcc
	s_addc_u32 s31, s27, s73
	s_lshl_b32 s26, s68, 6
	global_load_dwordx4 v[98:101], v[2:3], off
	global_load_dwordx4 v[102:105], v[4:5], off offset:32
	global_load_dwordx4 v[106:109], v[4:5], off offset:64
	global_load_dwordx4 v[110:113], v[4:5], off offset:96
	global_load_dwordx4 v[114:117], v[4:5], off offset:128
	global_load_dwordx4 v[118:121], v[4:5], off offset:160
	global_load_dwordx4 v[122:125], v[4:5], off offset:192
	global_load_dwordx4 v[126:129], v[4:5], off offset:224
	v_ashrrev_i32_e32 v2, 31, v38
	s_and_b32 s28, s26, 0xffffff80
	v_lshrrev_b32_e32 v2, 28, v2
	s_ashr_i32 s29, s28, 31
	v_add_u32_e32 v2, v38, v2
	s_lshl_b64 s[26:27], s[28:29], 1
	v_ashrrev_i32_e32 v39, 4, v2
	v_and_b32_e32 v2, -16, v2
	v_add_u32_e32 v13, 0x200, v38
	s_add_u32 s29, s30, s26
	v_sub_u32_e32 v12, v38, v2
	v_ashrrev_i32_e32 v2, 31, v13
	s_addc_u32 s30, s31, s27
	v_lshlrev_b32_e32 v6, 1, v8
	v_lshrrev_b32_e32 v2, 28, v2
	s_add_u32 s42, s29, 0x1400
	v_and_b32_e32 v9, 8, v6
	v_lshrrev_b32_e32 v6, 1, v8
	v_add_u32_e32 v2, v13, v2
	s_addc_u32 s43, s30, 0
	v_and_b32_e32 v10, 4, v6
	v_ashrrev_i32_e32 v40, 4, v2
	v_and_b32_e32 v2, -16, v2
	v_lshlrev_b32_e32 v6, 3, v12
	v_sub_u32_e32 v14, v13, v2
	v_mov_b64_e32 v[2:3], s[42:43]
	v_ashrrev_i32_e32 v7, 31, v6
	v_mad_i64_i32 v[4:5], s[42:43], v39, s84, v[2:3]
	v_lshlrev_b64 v[34:35], 1, v[6:7]
	v_lshl_add_u64 v[4:5], v[4:5], 0, v[34:35]
	s_addk_i32 s28, 0x200
	global_load_dwordx4 v[130:133], v[4:5], off
	v_lshlrev_b32_e32 v4, 3, v14
	s_mul_hi_i32 s31, s28, 0xc000
	s_mul_i32 s30, s28, 0xc000
	v_readlane_b32 s28, v251, 59
	v_ashrrev_i32_e32 v5, 31, v4
	v_readlane_b32 s29, v251, 60
	s_add_u32 s34, s28, s30
	v_mad_i64_i32 v[2:3], s[42:43], v40, s84, v[2:3]
	v_lshlrev_b64 v[36:37], 1, v[4:5]
	s_addc_u32 s35, s29, s31
	s_lshl_b64 s[28:29], s[24:25], 1
	v_lshl_add_u64 v[2:3], v[2:3], 0, v[36:37]
	s_add_u32 s34, s34, s28
	global_load_dwordx4 v[134:137], v[2:3], off
	v_lshlrev_b32_e32 v2, 4, v38
	s_addc_u32 s35, s35, s29
	v_and_b32_e32 v148, 0x70, v2
	v_mov_b32_e32 v149, v1
	v_lshl_add_u64 v[2:3], s[34:35], 0, v[148:149]
	v_ashrrev_i32_e32 v41, 3, v38
	v_mad_i64_i32 v[4:5], s[34:35], v41, s85, v[2:3]
	v_ashrrev_i32_e32 v46, 3, v13
	global_load_dwordx4 v[138:141], v[4:5], off
	v_mad_i64_i32 v[2:3], s[34:35], v46, s85, v[2:3]
	global_load_dwordx4 v[142:145], v[2:3], off
	s_movk_i32 s34, 0x110
	v_mul_lo_u32 v149, v39, s34
	v_lshlrev_b32_e32 v159, 4, v12
	v_add3_u32 v2, 0, v149, v159
	v_mul_lo_u32 v160, v40, s34
	v_lshlrev_b32_e32 v161, 4, v14
	s_movk_i32 s35, 0x90
	v_mul_lo_u32 v162, v41, s35
	v_mul_lo_u32 v163, v46, s35
	v_and_b32_e32 v11, 19, v8
	v_mul_u32_u24_e32 v166, 0x90, v0
	s_mov_b32 s35, 0xc2700000
	s_mov_b32 s40, 0
	s_mov_b32 s41, s40
	s_mov_b32 s42, s40
	s_mov_b32 s43, s40
	s_mov_b32 s44, s40
	s_mov_b32 s45, s40
	s_mov_b32 s46, s40
	s_mov_b32 s47, s40
	s_mov_b32 s48, s40
	s_mov_b32 s49, s40
	s_mov_b32 s50, s40
	s_mov_b32 s51, s40
	s_mov_b32 s52, s40
	s_mov_b32 s53, s40
	s_mov_b32 s54, s40
	s_mov_b32 s55, s40
	s_add_u32 s26, s26, s74
	s_addc_u32 s27, s27, s73
	s_mov_b64 s[74:75], 0x100
	v_mov_b32_e32 v169, 0
	s_waitcnt vmcnt(3)
	ds_write_b128 v2, v[130:133]
	v_add3_u32 v2, 0, v160, v161
	s_waitcnt vmcnt(2)
	ds_write_b128 v2, v[134:137]
	v_add_u32_e32 v2, 0, v148
	v_add_u32_e32 v3, v2, v162
	v_add_u32_e32 v2, v2, v163
	s_waitcnt vmcnt(1)
	ds_write_b128 v3, v[138:141] offset:17408
	v_ashrrev_i32_e32 v3, 1, v8
	v_and_b32_e32 v164, -16, v3
	s_waitcnt vmcnt(0)
	ds_write_b128 v2, v[142:145] offset:17408
	v_or3_b32 v2, v11, v9, v10
	v_mad_u32_u24 v165, v2, s34, v164
	v_add_u32_e32 v0, 0, v165
	s_waitcnt lgkmcnt(0)
	s_barrier
	ds_read_b128 v[18:21], v0
	ds_read_b128 v[42:45], v0 offset:32
	s_waitcnt lgkmcnt(1)
	v_mfma_f32_32x32x16_bf16 v[18:33], v[18:21], v[98:101], 0
	v_mov_b64_e32 v[2:3], s[40:41]
	v_mov_b64_e32 v[4:5], s[42:43]
	v_mov_b64_e32 v[6:7], s[44:45]
	v_mov_b64_e32 v[8:9], s[46:47]
	v_mov_b64_e32 v[10:11], s[48:49]
	v_mov_b64_e32 v[12:13], s[50:51]
	v_mov_b64_e32 v[14:15], s[52:53]
	s_waitcnt lgkmcnt(0)
	v_mfma_f32_32x32x16_bf16 v[18:33], v[42:45], v[102:105], v[18:33]
	ds_read_b128 v[42:45], v0 offset:64
	v_mov_b64_e32 v[16:17], s[54:55]
	s_mov_b64 s[42:43], 0x1e500080
	v_mov_b64_e32 v[64:65], v[16:17]
	s_mov_b64 s[44:45], 0xa0000
	s_mov_b32 s34, 64
	v_mov_b64_e32 v[62:63], v[14:15]
	s_waitcnt lgkmcnt(0)
	v_mfma_f32_32x32x16_bf16 v[18:33], v[42:45], v[106:109], v[18:33]
	ds_read_b128 v[42:45], v0 offset:96
	v_mov_b64_e32 v[60:61], v[12:13]
	v_mov_b64_e32 v[58:59], v[10:11]
	v_mov_b64_e32 v[56:57], v[8:9]
	v_mov_b64_e32 v[54:55], v[6:7]
	v_mov_b64_e32 v[52:53], v[4:5]
	v_mov_b64_e32 v[50:51], v[2:3]
	s_waitcnt lgkmcnt(0)
	v_mfma_f32_32x32x16_bf16 v[18:33], v[42:45], v[110:113], v[18:33]
	ds_read_b128 v[42:45], v0 offset:128
	s_waitcnt lgkmcnt(0)
	v_mfma_f32_32x32x16_bf16 v[18:33], v[42:45], v[114:117], v[18:33]
	ds_read_b128 v[42:45], v0 offset:160
	s_waitcnt lgkmcnt(0)
	v_mfma_f32_32x32x16_bf16 v[18:33], v[42:45], v[118:121], v[18:33]
	ds_read_b128 v[42:45], v0 offset:192
	s_waitcnt lgkmcnt(0)
	v_mfma_f32_32x32x16_bf16 v[18:33], v[42:45], v[122:125], v[18:33]
	ds_read_b128 v[42:45], v0 offset:224
	s_waitcnt lgkmcnt(0)
	v_mfma_f32_32x32x16_bf16 v[18:33], v[42:45], v[126:129], v[18:33]
	s_nop 11
	v_max_f32_e32 v0, v18, v19
	v_max3_f32 v0, v0, v20, v21
	v_max3_f32 v0, v0, v22, v23
	v_max3_f32 v0, v0, v24, v25
	v_and_b32_e32 v19, 64, v210
	v_max3_f32 v0, v0, v26, v27
	v_xor_b32_e32 v18, 32, v210
	v_add_u32_e32 v19, 64, v19
	v_max3_f32 v0, v0, v28, v29
	v_cmp_lt_i32_e32 vcc, v18, v19
	v_max3_f32 v0, v0, v30, v31
	v_max3_f32 v0, v0, v32, v33
	v_cndmask_b32_e32 v18, v210, v18, vcc
	v_lshlrev_b32_e32 v167, 2, v18
	ds_bpermute_b32 v18, v167, v0
	s_waitcnt lgkmcnt(0)
	v_max3_f32 v168, v0, v18, s35
	v_mov_b64_e32 v[18:19], s[30:31]
	v_and_b32_e32 v0, 7, v38
	v_mad_i64_i32 v[20:21], s[30:31], v46, s85, v[18:19]
	v_lshlrev_b32_e32 v0, 4, v0
	v_mad_i64_i32 v[18:19], s[30:31], v41, s85, v[18:19]
	v_lshl_add_u64 v[18:19], v[18:19], 0, v[0:1]
	v_lshl_add_u64 v[20:21], v[20:21], 0, v[0:1]
	v_lshl_add_u64 v[18:19], v[18:19], 0, s[28:29]
	v_lshl_add_u64 v[20:21], v[20:21], 0, s[28:29]
	v_lshl_add_u64 v[152:153], v[18:19], 0, s[42:43]
	v_mov_b64_e32 v[18:19], s[26:27]
	v_lshl_add_u64 v[150:151], v[20:21], 0, s[42:43]
	v_mad_i64_i32 v[20:21], s[26:27], v39, s84, v[18:19]
	v_mad_i64_i32 v[18:19], s[26:27], v40, s84, v[18:19]
	v_lshl_add_u64 v[20:21], v[20:21], 0, v[34:35]
	s_mov_b64 s[28:29], 0xf5a1400
	v_lshl_add_u64 v[18:19], v[18:19], 0, v[36:37]
	v_lshl_add_u64 v[154:155], v[20:21], 0, s[28:29]
	v_lshl_add_u64 v[156:157], v[18:19], 0, s[28:29]
	v_mov_b64_e32 v[32:33], v[16:17]
	v_mov_b64_e32 v[48:49], v[16:17]
	v_mov_b64_e32 v[30:31], v[14:15]
	v_mov_b64_e32 v[28:29], v[12:13]
	v_mov_b64_e32 v[26:27], v[10:11]
	v_mov_b64_e32 v[24:25], v[8:9]
	v_mov_b64_e32 v[22:23], v[6:7]
	v_mov_b64_e32 v[20:21], v[4:5]
	v_mov_b64_e32 v[18:19], v[2:3]
	v_mov_b64_e32 v[46:47], v[14:15]
	v_mov_b64_e32 v[44:45], v[12:13]
	v_mov_b64_e32 v[42:43], v[10:11]
	v_mov_b64_e32 v[40:41], v[8:9]
	v_mov_b64_e32 v[38:39], v[6:7]
	v_mov_b64_e32 v[36:37], v[4:5]
	v_mov_b64_e32 v[34:35], v[2:3]
	s_branch .LBB0_67

.LBB0_69:
	s_mul_i32 s30, s40, 0xac00
	s_add_i32 s30, s30, 0
	v_add_u32_e32 v188, s30, v165
	ds_read_b128 v[170:173], v188
	ds_read_b128 v[174:177], v188 offset:32
	ds_read_b128 v[178:181], v188 offset:64
	v_xor_b32_e32 v66, 0x80000000, v168
	v_mov_b32_e32 v67, v66
	v_mov_b32_e32 v68, v66
	v_mov_b32_e32 v69, v66
	v_mov_b32_e32 v70, v66
	v_mov_b32_e32 v71, v66
	v_mov_b32_e32 v72, v66
	v_mov_b32_e32 v73, v66
	v_mov_b32_e32 v74, v66
	v_mov_b32_e32 v75, v66
	v_mov_b32_e32 v76, v66
	v_mov_b32_e32 v77, v66
	v_mov_b32_e32 v78, v66
	v_mov_b32_e32 v79, v66
	v_mov_b32_e32 v80, v66
	v_mov_b32_e32 v81, v66
	s_waitcnt lgkmcnt(2)
	s_nop 0
	v_mfma_f32_32x32x16_bf16 v[82:97], v[170:173], v[98:101], v[66:81]
	ds_read_b128 v[170:173], v188 offset:96
	s_waitcnt lgkmcnt(2)
	v_mfma_f32_32x32x16_bf16 v[82:97], v[174:177], v[102:105], v[82:97]
	ds_read_b128 v[174:177], v188 offset:128
	s_waitcnt lgkmcnt(2)
	v_mfma_f32_32x32x16_bf16 v[82:97], v[178:181], v[106:109], v[82:97]
	ds_read_b128 v[178:181], v188 offset:160
	s_waitcnt lgkmcnt(2)
	v_mfma_f32_32x32x16_bf16 v[82:97], v[170:173], v[110:113], v[82:97]
	ds_read_b128 v[170:173], v188 offset:192
	s_waitcnt lgkmcnt(2)
	v_mfma_f32_32x32x16_bf16 v[82:97], v[174:177], v[114:117], v[82:97]
	ds_read_b128 v[174:177], v188 offset:224
	s_waitcnt lgkmcnt(2)
	v_mfma_f32_32x32x16_bf16 v[82:97], v[178:181], v[118:121], v[82:97]
	ds_read_b128 v[178:181], v188 offset:8704
	s_waitcnt lgkmcnt(2)
	v_mfma_f32_32x32x16_bf16 v[82:97], v[170:173], v[122:125], v[82:97]
	ds_read_b128 v[170:173], v188 offset:8736
	s_waitcnt lgkmcnt(2)
	v_mfma_f32_32x32x16_bf16 v[82:97], v[174:177], v[126:129], v[82:97]
	ds_read_b128 v[174:177], v188 offset:8768
	v_add3_u32 v189, s30, v166, v164
	ds_read_b128 v[182:185], v188 offset:8800
	s_waitcnt lgkmcnt(3)
	v_mfma_f32_32x32x16_bf16 v[66:81], v[178:181], v[98:101], v[66:81]
	s_nop 6
	v_exp_f32_e32 v0, v82
	v_exp_f32_e32 v178, v83
	v_max_f32_e32 v83, v82, v83
	v_add_f32_e32 v187, v0, v178
	v_cvt_pk_bf16_f32 v82, v0, v178
	ds_read_b128 v[178:181], v188 offset:8832
	s_waitcnt lgkmcnt(3)
	v_mfma_f32_32x32x16_bf16 v[66:81], v[170:173], v[102:105], v[66:81]
	v_exp_f32_e32 v186, v84
	v_exp_f32_e32 v0, v85
	v_max_f32_e32 v84, v84, v85
	v_max3_f32 v190, v83, s86, v84
	v_pk_add_f32 v[84:85], v[186:187], v[0:1]
	v_cvt_pk_bf16_f32 v83, v186, v0
	v_pk_add_f32 v[186:187], v[84:85], v[84:85] op_sel_hi:[0,1]
	ds_read_b128 v[170:173], v188 offset:8864
	s_waitcnt lgkmcnt(3)
	v_mfma_f32_32x32x16_bf16 v[66:81], v[174:177], v[106:109], v[66:81]
	v_exp_f32_e32 v84, v86
	v_exp_f32_e32 v85, v87
	v_max_f32_e32 v0, v86, v87
	v_add_f32_e32 v87, v84, v85
	v_cvt_pk_bf16_f32 v84, v84, v85
	ds_read_b128 v[174:177], v188 offset:8896
	s_waitcnt lgkmcnt(3)
	v_mfma_f32_32x32x16_bf16 v[66:81], v[182:185], v[110:113], v[66:81]
	v_exp_f32_e32 v86, v88
	v_exp_f32_e32 v186, v89
	v_max_f32_e32 v85, v88, v89
	v_pk_add_f32 v[88:89], v[86:87], v[186:187]
	v_max3_f32 v0, v190, v0, v85
	v_cvt_pk_bf16_f32 v85, v86, v186
	v_pk_add_f32 v[186:187], v[88:89], v[88:89] op_sel_hi:[0,1]
	ds_read_b128 v[86:89], v188 offset:8928
	s_waitcnt lgkmcnt(3)
	v_mfma_f32_32x32x16_bf16 v[66:81], v[178:181], v[114:117], v[66:81]
	v_exp_f32_e32 v182, v90
	v_exp_f32_e32 v184, v91
	v_max_f32_e32 v91, v90, v91
	v_add_f32_e32 v183, v182, v184
	v_cvt_pk_bf16_f32 v90, v182, v184
	ds_read_b128 v[178:181], v189 offset:17408
	s_waitcnt lgkmcnt(3)
	v_mfma_f32_32x32x16_bf16 v[66:81], v[170:173], v[118:121], v[66:81]
	v_exp_f32_e32 v182, v92
	v_exp_f32_e32 v186, v93
	v_max_f32_e32 v92, v92, v93
	v_max3_f32 v0, v0, v91, v92
	v_pk_add_f32 v[92:93], v[182:183], v[186:187]
	v_cvt_pk_bf16_f32 v91, v182, v186
	v_pk_add_f32 v[182:183], v[92:93], v[92:93] op_sel_hi:[0,1]
	ds_read_b128 v[170:173], v189 offset:22016
	s_waitcnt lgkmcnt(3)
	v_mfma_f32_32x32x16_bf16 v[66:81], v[174:177], v[122:125], v[66:81]
	v_exp_f32_e32 v93, v94
	v_exp_f32_e32 v182, v95
	v_max_f32_e32 v184, v94, v95
	v_add_f32_e32 v95, v93, v182
	v_cvt_pk_bf16_f32 v92, v93, v182
	ds_read_b128 v[174:177], v189 offset:26624
	s_waitcnt lgkmcnt(3)
	v_mfma_f32_32x32x16_bf16 v[66:81], v[86:89], v[126:129], v[66:81]
	v_exp_f32_e32 v94, v96
	v_exp_f32_e32 v182, v97
	v_max_f32_e32 v86, v96, v97
	v_max3_f32 v0, v0, v184, v86
	v_pk_add_f32 v[86:87], v[94:95], v[182:183]
	v_cvt_pk_bf16_f32 v93, v94, v182
	v_pk_add_f32 v[182:183], v[86:87], v[86:87] op_sel_hi:[0,1]
	ds_read_b128 v[86:89], v189 offset:31232
	ds_read_b128 v[94:97], v189 offset:17440
	s_waitcnt lgkmcnt(4)
	v_mfma_f32_32x32x16_bf16 v[50:65], v[178:181], v[82:85], v[50:65]
	s_nop 0
	v_exp_f32_e32 v178, v66
	v_exp_f32_e32 v179, v67
	v_max_f32_e32 v67, v66, v67
	v_add_f32_e32 v185, v178, v179
	v_cvt_pk_bf16_f32 v66, v178, v179
	ds_read_b128 v[178:181], v189 offset:22048
	s_waitcnt lgkmcnt(4)
	v_mfma_f32_32x32x16_bf16 v[34:49], v[170:173], v[82:85], v[34:49]
	v_exp_f32_e32 v182, v68
	v_exp_f32_e32 v184, v69
	v_max_f32_e32 v68, v68, v69
	v_max3_f32 v0, v0, v67, v68
	v_pk_add_f32 v[68:69], v[182:183], v[184:185]
	v_cvt_pk_bf16_f32 v67, v182, v184
	v_pk_add_f32 v[182:183], v[68:69], v[68:69] op_sel_hi:[0,1]
	ds_read_b128 v[170:173], v189 offset:26656
	s_waitcnt lgkmcnt(4)
	v_mfma_f32_32x32x16_bf16 v[18:33], v[174:177], v[82:85], v[18:33]
	v_exp_f32_e32 v68, v70
	v_exp_f32_e32 v69, v71
	v_max_f32_e32 v184, v70, v71
	v_add_f32_e32 v71, v68, v69
	v_cvt_pk_bf16_f32 v68, v68, v69
	ds_read_b128 v[174:177], v189 offset:31264
	s_waitcnt lgkmcnt(4)
	v_mfma_f32_32x32x16_bf16 v[2:17], v[86:89], v[82:85], v[2:17]
	v_exp_f32_e32 v70, v72
	v_exp_f32_e32 v182, v73
	v_max_f32_e32 v69, v72, v73
	v_pk_add_f32 v[72:73], v[70:71], v[182:183]
	v_max3_f32 v0, v0, v184, v69
	v_pk_add_f32 v[72:73], v[72:73], v[72:73] op_sel_hi:[0,1]
	v_cvt_pk_bf16_f32 v69, v70, v182
	s_waitcnt lgkmcnt(3)
	v_mfma_f32_32x32x16_bf16 v[50:65], v[94:97], v[90:93], v[50:65]
	v_exp_f32_e32 v70, v74
	v_exp_f32_e32 v71, v75
	v_max_f32_e32 v86, v74, v75
	v_add_f32_e32 v75, v70, v71
	v_cvt_pk_bf16_f32 v70, v70, v71
	v_exp_f32_e32 v74, v76
	v_exp_f32_e32 v72, v77
	v_max_f32_e32 v71, v76, v77
	v_pk_add_f32 v[76:77], v[74:75], v[72:73]
	v_max3_f32 v0, v0, v86, v71
	v_pk_add_f32 v[94:95], v[76:77], v[76:77] op_sel_hi:[0,1]
	v_cvt_pk_bf16_f32 v71, v74, v72
	ds_read_b128 v[74:77], v189 offset:22080
	s_waitcnt lgkmcnt(3)
	v_mfma_f32_32x32x16_bf16 v[34:49], v[178:181], v[90:93], v[34:49]
	ds_read_b128 v[82:85], v189 offset:17472
	s_waitcnt lgkmcnt(1)
	v_mfma_f32_32x32x16_bf16 v[34:49], v[74:77], v[66:69], v[34:49]
	ds_read_b128 v[74:77], v189 offset:26720
	v_mfma_f32_32x32x16_bf16 v[18:33], v[170:173], v[90:93], v[18:33]
	v_exp_f32_e32 v72, v78
	v_exp_f32_e32 v73, v79
	v_max_f32_e32 v170, v78, v79
	v_add_f32_e32 v79, v72, v73
	v_cvt_pk_bf16_f32 v72, v72, v73
	v_exp_f32_e32 v78, v80
	v_exp_f32_e32 v94, v81
	ds_read_b128 v[86:89], v189 offset:26688
	v_max_f32_e32 v171, v80, v81
	v_pk_add_f32 v[96:97], v[78:79], v[94:95]
	v_cvt_pk_bf16_f32 v73, v78, v94
	ds_read_b128 v[78:81], v189 offset:17504
	s_waitcnt lgkmcnt(3)
	v_mfma_f32_32x32x16_bf16 v[50:65], v[82:85], v[66:69], v[50:65]
	ds_read_b128 v[82:85], v189 offset:31296
	v_mfma_f32_32x32x16_bf16 v[2:17], v[174:177], v[90:93], v[2:17]
	ds_read_b128 v[90:93], v189 offset:22112
	s_waitcnt lgkmcnt(3)
	v_mfma_f32_32x32x16_bf16 v[18:33], v[86:89], v[66:69], v[18:33]
	ds_read_b128 v[86:89], v189 offset:31328
	s_waitcnt lgkmcnt(2)
	v_mfma_f32_32x32x16_bf16 v[2:17], v[82:85], v[66:69], v[2:17]
	v_mfma_f32_32x32x16_bf16 v[50:65], v[78:81], v[70:73], v[50:65]
	s_waitcnt lgkmcnt(1)
	v_mfma_f32_32x32x16_bf16 v[34:49], v[90:93], v[70:73], v[34:49]
	v_mfma_f32_32x32x16_bf16 v[18:33], v[74:77], v[70:73], v[18:33]
	s_waitcnt lgkmcnt(0)
	v_mfma_f32_32x32x16_bf16 v[2:17], v[86:89], v[70:73], v[2:17]
	v_max3_f32 v0, v0, v170, v171
	ds_bpermute_b32 v66, v167, v0
	v_add_f32_e32 v67, v96, v97
	v_add_f32_e32 v169, v169, v67
	s_waitcnt lgkmcnt(0)
	v_max_f32_e32 v66, v66, v66
	v_max_f32_e32 v0, v0, v66
	v_cmp_lt_f32_e32 vcc, s87, v0
	s_cbranch_vccz .LBB0_71
	v_max_f32_e32 v0, v0, v0
	v_max_f32_e32 v66, 0, v0
	v_exp_f32_e64 v0, -v66
	v_add_f32_e32 v168, v168, v66
	v_mul_f32_e32 v169, v169, v0
	v_pk_mul_f32 v[64:65], v[64:65], v[0:1] op_sel_hi:[1,0]
	v_pk_mul_f32 v[62:63], v[62:63], v[0:1] op_sel_hi:[1,0]
	v_pk_mul_f32 v[60:61], v[60:61], v[0:1] op_sel_hi:[1,0]
	v_pk_mul_f32 v[58:59], v[58:59], v[0:1] op_sel_hi:[1,0]
	v_pk_mul_f32 v[56:57], v[56:57], v[0:1] op_sel_hi:[1,0]
	v_pk_mul_f32 v[54:55], v[54:55], v[0:1] op_sel_hi:[1,0]
	v_pk_mul_f32 v[52:53], v[52:53], v[0:1] op_sel_hi:[1,0]
	v_pk_mul_f32 v[50:51], v[50:51], v[0:1] op_sel_hi:[1,0]
	v_pk_mul_f32 v[48:49], v[48:49], v[0:1] op_sel_hi:[1,0]
	v_pk_mul_f32 v[46:47], v[46:47], v[0:1] op_sel_hi:[1,0]
	v_pk_mul_f32 v[44:45], v[44:45], v[0:1] op_sel_hi:[1,0]
	v_pk_mul_f32 v[42:43], v[42:43], v[0:1] op_sel_hi:[1,0]
	v_pk_mul_f32 v[40:41], v[40:41], v[0:1] op_sel_hi:[1,0]
	v_pk_mul_f32 v[38:39], v[38:39], v[0:1] op_sel_hi:[1,0]
	v_pk_mul_f32 v[36:37], v[36:37], v[0:1] op_sel_hi:[1,0]
	v_pk_mul_f32 v[34:35], v[34:35], v[0:1] op_sel_hi:[1,0]
	v_pk_mul_f32 v[32:33], v[32:33], v[0:1] op_sel_hi:[1,0]
	v_pk_mul_f32 v[30:31], v[30:31], v[0:1] op_sel_hi:[1,0]
	v_pk_mul_f32 v[28:29], v[28:29], v[0:1] op_sel_hi:[1,0]
	v_pk_mul_f32 v[26:27], v[26:27], v[0:1] op_sel_hi:[1,0]
	v_pk_mul_f32 v[24:25], v[24:25], v[0:1] op_sel_hi:[1,0]
	v_pk_mul_f32 v[22:23], v[22:23], v[0:1] op_sel_hi:[1,0]
	v_pk_mul_f32 v[20:21], v[20:21], v[0:1] op_sel_hi:[1,0]
	v_pk_mul_f32 v[18:19], v[18:19], v[0:1] op_sel_hi:[1,0]
	v_pk_mul_f32 v[16:17], v[16:17], v[0:1] op_sel_hi:[1,0]
	v_pk_mul_f32 v[14:15], v[14:15], v[0:1] op_sel_hi:[1,0]
	v_pk_mul_f32 v[12:13], v[12:13], v[0:1] op_sel_hi:[1,0]
	v_pk_mul_f32 v[10:11], v[10:11], v[0:1] op_sel_hi:[1,0]
	v_pk_mul_f32 v[8:9], v[8:9], v[0:1] op_sel_hi:[1,0]
	v_pk_mul_f32 v[6:7], v[6:7], v[0:1] op_sel_hi:[1,0]
	v_pk_mul_f32 v[4:5], v[4:5], v[0:1] op_sel_hi:[1,0]
	v_pk_mul_f32 v[2:3], v[2:3], v[0:1] op_sel_hi:[1,0]

.LBB0_88:
	s_mov_b64 s[0:1], -1
	s_cmp_lg_u32 s72, 1
	s_mul_i32 s26, s68, 0x600000
	s_cbranch_scc0 .LBB0_101
	s_add_i32 s47, s70, s60
	s_ashr_i32 s0, s47, 31
	s_add_u32 s42, s47, s24
	s_addc_u32 s43, s0, s25
	s_lshl_b32 s28, s68, 7
	s_ashr_i32 s29, s28, 31
	s_lshl_b64 s[0:1], s[28:29], 1
	s_mul_i32 s49, s24, 0x2800
	v_readlane_b32 s54, v251, 57
	s_mul_hi_i32 s48, s24, 0x2800
	v_readlane_b32 s55, v251, 58
	s_add_u32 s27, s54, s49
	s_addc_u32 s34, s55, s48
	s_add_u32 s44, s27, s0
	s_addc_u32 s45, s34, s1
	v_readlane_b32 s34, v251, 59
	s_mul_hi_i32 s27, s28, 0xc000
	v_readlane_b32 s35, v251, 60
	s_add_u32 s34, s34, s26
	s_addc_u32 s35, s35, s27
	s_lshl_b64 s[40:41], s[24:25], 1
	s_add_u32 s50, s34, s40
	s_addc_u32 s51, s35, s41
	s_lshl_b32 s34, s68, 14
	s_ashr_i32 s35, s34, 31
	s_lshl_b64 s[34:35], s[34:35], 2
	v_readlane_b32 s52, v254, 27
	v_readlane_b32 s53, v254, 28
	s_add_u32 s52, s52, s34
	v_mov_b32_e32 v228, v222
	s_addc_u32 s53, s53, s35
	v_mov_b32_e32 v0, 0x7000
	s_nop 0
	global_load_dword v229, v0, s[52:53] offset:1296
	v_mov_b32_e32 v0, 0x8000
	v_mov_b32_e32 v34, v223
	global_load_dword v230, v0, s[52:53] offset:2800
	v_mov_b32_e32 v195, v1
	v_ashrrev_i32_e32 v0, 31, v34
	v_lshrrev_b32_e32 v0, 28, v0
	v_add_u32_e32 v0, v34, v0
	v_ashrrev_i32_e32 v36, 4, v0
	v_and_b32_e32 v0, -16, v0
	v_sub_u32_e32 v8, v34, v0
	v_add_u32_e32 v0, 0x200, v34
	v_ashrrev_i32_e32 v2, 31, v0
	v_lshrrev_b32_e32 v2, 28, v2
	v_add_u32_e32 v2, v0, v2
	v_ashrrev_i32_e32 v37, 4, v2
	v_and_b32_e32 v2, -16, v2
	v_lshlrev_b32_e32 v6, 3, v8
	v_sub_u32_e32 v9, v0, v2
	v_ashrrev_i32_e32 v7, 31, v6
	v_lshlrev_b64 v[26:27], 1, v[6:7]
	v_lshlrev_b32_e32 v6, 3, v9
	v_mov_b64_e32 v[2:3], s[44:45]
	v_ashrrev_i32_e32 v7, 31, v6
	v_mad_i64_i32 v[4:5], s[44:45], v36, s84, v[2:3]
	v_mad_i64_i32 v[2:3], s[44:45], v37, s84, v[2:3]
	v_lshlrev_b64 v[28:29], 1, v[6:7]
	v_lshl_add_u64 v[4:5], v[4:5], 0, v[26:27]
	v_lshl_add_u64 v[2:3], v[2:3], 0, v[28:29]
	global_load_dwordx4 v[148:151], v[4:5], off offset:1024
	global_load_dwordx4 v[152:155], v[2:3], off offset:1024
	v_lshlrev_b32_e32 v2, 4, v34
	v_and_b32_e32 v194, 0x70, v2
	v_lshl_add_u64 v[2:3], s[50:51], 0, v[194:195]
	v_ashrrev_i32_e32 v35, 3, v34
	v_mad_i64_i32 v[4:5], s[44:45], v35, s85, v[2:3]
	v_ashrrev_i32_e32 v38, 3, v0
	v_mad_i64_i32 v[2:3], s[44:45], v38, s85, v[2:3]
	global_load_dwordx4 v[156:159], v[4:5], off
	global_load_dwordx4 v[160:163], v[2:3], off
	v_and_b32_e32 v0, 31, v228
	v_lshl_add_u64 v[192:193], s[42:43], 0, v[0:1]
	v_mov_b64_e32 v[2:3], s[54:55]
	v_mad_u64_u32 v[2:3], s[42:43], v192, s84, v[2:3]
	v_ashrrev_i32_e32 v226, 5, v228
	v_mad_i32_i24 v3, v193, s84, v3
	v_lshl_add_u64 v[2:3], v[2:3], 0, s[0:1]
	v_lshlrev_b32_e32 v30, 3, v226
	v_lshl_add_u64 v[2:3], s[14:15], 1, v[2:3]
	v_ashrrev_i32_e32 v31, 31, v30
	v_lshl_add_u64 v[2:3], v[30:31], 1, v[2:3]
	global_load_dwordx4 v[164:167], v[2:3], off
	global_load_dwordx4 v[168:171], v[2:3], off offset:32
	global_load_dwordx4 v[172:175], v[2:3], off offset:64
	global_load_dwordx4 v[176:179], v[2:3], off offset:96
	v_lshlrev_b32_e32 v2, 1, v228
	v_lshrrev_b32_e32 v3, 1, v228
	v_and_b32_e32 v4, 19, v228
	v_and_b32_e32 v2, 8, v2
	v_and_b32_e32 v3, 4, v3
	s_movk_i32 s43, 0x90
	s_movk_i32 s42, 0x110
	v_or3_b32 v2, v4, v2, v3
	v_mul_lo_u32 v231, v35, s43
	v_add_u32_e32 v3, 0, v194
	v_mul_lo_u32 v232, v38, s43
	v_mul_lo_u32 v233, v36, s42
	v_lshlrev_b32_e32 v234, 4, v8
	v_add_u32_e32 v4, v3, v231
	v_add_u32_e32 v3, v3, v232
	v_mul_lo_u32 v235, v37, s42
	v_add3_u32 v5, 0, v233, v234
	v_lshlrev_b32_e32 v236, 4, v9
	v_add3_u32 v6, 0, v235, v236
	v_mul_u32_u24_e32 v2, 0x110, v2
	v_and_b32_e32 v23, 64, v210
	v_xor_b32_e32 v22, 32, v210
	v_add_u32_e32 v227, 64, v23
	v_cmp_lt_i32_e32 vcc, v22, v227
	v_add_u32_e32 v32, s47, v0
	s_add_i32 s46, s47, 0x25f
	v_cndmask_b32_e32 v33, v210, v22, vcc
	v_lshlrev_b32_e32 v195, 2, v33
	s_waitcnt vmcnt(0)
	ds_write_b128 v5, v[148:151]
	s_waitcnt vmcnt(6)
	ds_write_b128 v6, v[152:155]
	s_waitcnt vmcnt(5)
	ds_write_b128 v4, v[156:159] offset:17408
	s_waitcnt vmcnt(4)
	ds_write_b128 v3, v[160:163] offset:17408
	v_ashrrev_i32_e32 v3, 1, v228
	v_and_b32_e32 v39, -16, v3
	v_add3_u32 v237, v39, s61, v2
	v_add_u32_e32 v40, 0, v237
	s_waitcnt lgkmcnt(0)
	s_barrier
	ds_read_b128 v[2:5], v40
	ds_read_b128 v[18:21], v40 offset:32
	s_waitcnt vmcnt(3) lgkmcnt(1)
	v_mfma_f32_32x32x16_bf16 v[2:17], v[2:5], v[164:167], 0
	ds_read_b128 v[22:25], v40 offset:64
	v_mad_u32_u24 v238, v0, s43, v39
	v_and_b32_e32 v0, 7, v34
	v_lshlrev_b32_e32 v0, 4, v0
	s_addk_i32 s47, 0xfd81
	s_add_u32 s0, s0, s49
	s_addc_u32 s1, s1, s48
	s_waitcnt vmcnt(2) lgkmcnt(1)
	v_mfma_f32_32x32x16_bf16 v[2:17], v[18:21], v[168:171], v[2:17]
	ds_read_b128 v[18:21], v40 offset:96
	v_ashrrev_i32_e32 v33, 31, v32
	v_mov_b32_e32 v240, 0
	s_mov_b64 s[50:51], 0xa0000
	s_mov_b32 s44, 0
	s_mov_b32 s45, 64
	v_mov_b32_e32 v39, v240
	s_waitcnt vmcnt(1) lgkmcnt(1)
	v_mfma_f32_32x32x16_bf16 v[2:17], v[22:25], v[172:175], v[2:17]
	v_mov_b64_e32 v[22:23], s[26:27]
	v_mad_i64_i32 v[24:25], s[42:43], v38, s85, v[22:23]
	v_mad_i64_i32 v[22:23], s[42:43], v35, s85, v[22:23]
	v_lshl_add_u64 v[24:25], v[24:25], 0, v[0:1]
	v_lshl_add_u64 v[22:23], v[22:23], 0, v[0:1]
	s_waitcnt vmcnt(0) lgkmcnt(0)
	v_mfma_f32_32x32x16_bf16 v[2:17], v[18:21], v[176:179], v[2:17]
	v_mov_b64_e32 v[34:35], s[0:1]
	s_mov_b64 s[0:1], 0x1e500080
	v_mov_b32_e32 v18, 0
	v_mov_b32_e32 v19, v240
	v_mov_b32_e32 v20, v240
	v_mov_b32_e32 v21, v240
	v_mov_b32_e32 v38, v240
	s_nop 4
	v_max_f32_e32 v0, v2, v3
	v_max3_f32 v0, v0, v4, v5
	v_max3_f32 v0, v0, v6, v7
	v_max3_f32 v0, v0, v8, v9
	v_max3_f32 v0, v0, v10, v11
	v_max3_f32 v0, v0, v12, v13
	v_max3_f32 v0, v0, v14, v15
	v_max3_f32 v0, v0, v16, v17
	ds_bpermute_b32 v6, v195, v0
	v_lshl_add_u64 v[2:3], v[22:23], 0, s[40:41]
	v_lshl_add_u64 v[4:5], v[24:25], 0, s[40:41]
	v_lshl_add_u64 v[196:197], v[2:3], 0, s[0:1]
	v_lshl_add_u64 v[198:199], v[4:5], 0, s[0:1]
	s_mov_b32 s0, 0xc2700000
	s_waitcnt lgkmcnt(0)
	v_max3_f32 v239, v0, v6, s0
	v_mad_i64_i32 v[2:3], s[0:1], v37, s84, v[34:35]
	v_lshl_add_u64 v[2:3], v[2:3], 0, v[28:29]
	s_mov_b64 s[40:41], 0xf5a0400
	v_lshl_add_u64 v[200:201], v[2:3], 0, s[40:41]
	v_mad_i64_i32 v[2:3], s[0:1], v36, s84, v[34:35]
	s_add_u32 s0, s34, 0x18080
	v_lshl_add_u64 v[2:3], v[2:3], 0, v[26:27]
	s_addc_u32 s1, s35, 0
	v_lshl_add_u64 v[202:203], v[2:3], 0, s[40:41]
	v_lshl_add_u64 v[2:3], v[30:31], 2, s[0:1]
	v_lshlrev_b64 v[4:5], 2, v[32:33]
	v_sub_co_u32_e32 v204, vcc, v2, v4
	v_mov_b32_e32 v2, 0
	s_nop 0
	v_subb_co_u32_e32 v205, vcc, v3, v5, vcc
	v_mov_b32_e32 v3, v240
	v_mov_b32_e32 v4, v240
	v_mov_b32_e32 v5, v240
	v_mov_b32_e32 v6, v240
	v_mov_b32_e32 v7, v240
	v_mov_b32_e32 v8, v240
	v_mov_b32_e32 v9, v240
	v_mov_b32_e32 v10, v240
	v_mov_b32_e32 v11, v240
	v_mov_b32_e32 v12, v240
	v_mov_b32_e32 v13, v240
	v_mov_b32_e32 v14, v240
	v_mov_b32_e32 v15, v240
	v_mov_b32_e32 v16, v240
	v_mov_b32_e32 v17, v240
	v_mov_b32_e32 v22, v240
	v_mov_b32_e32 v23, v240
	v_mov_b32_e32 v24, v240
	v_mov_b32_e32 v25, v240
	v_mov_b32_e32 v26, v240
	v_mov_b32_e32 v27, v240
	v_mov_b32_e32 v28, v240
	v_mov_b32_e32 v29, v240
	v_mov_b32_e32 v30, v240
	v_mov_b32_e32 v31, v240
	v_mov_b32_e32 v32, v240
	v_mov_b32_e32 v33, v240
	v_mov_b32_e32 v34, 0
	v_mov_b32_e32 v35, v240
	v_mov_b32_e32 v36, v240
	v_mov_b32_e32 v37, v240
	v_mov_b32_e32 v40, v240
	v_mov_b32_e32 v41, v240
	v_mov_b32_e32 v42, v240
	v_mov_b32_e32 v43, v240
	v_mov_b32_e32 v44, v240
	v_mov_b32_e32 v45, v240
	v_mov_b32_e32 v46, v240
	v_mov_b32_e32 v47, v240
	v_mov_b32_e32 v48, v240
	v_mov_b32_e32 v49, v240
	v_mov_b32_e32 v50, 0
	v_mov_b32_e32 v51, v240
	v_mov_b32_e32 v52, v240
	v_mov_b32_e32 v53, v240
	v_mov_b32_e32 v54, v240
	v_mov_b32_e32 v55, v240
	v_mov_b32_e32 v56, v240
	v_mov_b32_e32 v57, v240
	v_mov_b32_e32 v58, v240
	v_mov_b32_e32 v59, v240
	v_mov_b32_e32 v60, v240
	v_mov_b32_e32 v61, v240
	v_mov_b32_e32 v62, v240
	v_mov_b32_e32 v63, v240
	v_mov_b32_e32 v64, v240
	v_mov_b32_e32 v65, v240
	s_branch .LBB0_91

.LBB0_93:
	s_mul_i32 s0, s44, 0xac00
	s_sub_i32 s27, s45, 64
	s_add_i32 s48, s0, 0
	s_cmp_gt_i32 s27, s47
	s_cselect_b64 s[0:1], -1, 0
	s_cmp_lt_i32 s27, s46
	v_sub_f32_e32 v0, v230, v239
	s_cselect_b64 s[42:43], -1, 0
	v_cndmask_b32_e64 v66, v0, -v239, s[42:43]
	s_and_b64 s[42:43], s[0:1], s[42:43]
	s_andn2_b64 vcc, exec, s[42:43]
	v_add_u32_e32 v242, s48, v237
	v_add_u32_e32 v241, s48, v238
	s_cbranch_vccz .LBB0_95
	v_sub_f32_e32 v0, v229, v239
	ds_read_b128 v[100:103], v242
	ds_read_b128 v[104:107], v242 offset:32
	ds_read_b128 v[108:111], v242 offset:64
	v_cndmask_b32_e64 v68, v0, v66, s[0:1]
	v_mov_b32_e32 v69, v68
	v_mov_b32_e32 v70, v68
	v_mov_b32_e32 v71, v68
	v_mov_b32_e32 v72, v68
	v_mov_b32_e32 v73, v68
	v_mov_b32_e32 v74, v68
	v_mov_b32_e32 v75, v68
	v_mov_b32_e32 v76, v68
	v_mov_b32_e32 v77, v68
	v_mov_b32_e32 v78, v68
	v_mov_b32_e32 v79, v68
	v_mov_b32_e32 v80, v68
	v_mov_b32_e32 v81, v68
	v_mov_b32_e32 v82, v68
	v_mov_b32_e32 v83, v68
	ds_read_b128 v[112:115], v242 offset:96
	s_waitcnt lgkmcnt(3)
	v_mfma_f32_32x32x16_bf16 v[84:99], v[100:103], v[164:167], v[68:83]
	ds_read_b128 v[116:119], v242 offset:8704
	s_waitcnt lgkmcnt(3)
	v_mfma_f32_32x32x16_bf16 v[84:99], v[104:107], v[168:171], v[84:99]
	ds_read_b128 v[120:123], v242 offset:8736
	s_waitcnt lgkmcnt(3)
	v_mfma_f32_32x32x16_bf16 v[84:99], v[108:111], v[172:175], v[84:99]
	ds_read_b128 v[244:247], v241 offset:31232
	ds_read_b128 v[104:107], v242 offset:8768
	s_waitcnt lgkmcnt(4)
	v_mfma_f32_32x32x16_bf16 v[84:99], v[112:115], v[176:179], v[84:99]
	ds_read_b128 v[100:103], v242 offset:8800
	s_waitcnt lgkmcnt(4)
	v_mfma_f32_32x32x16_bf16 v[68:83], v[116:119], v[164:167], v[68:83]
	s_nop 8
	v_max_f32_e32 v0, v84, v85
	v_exp_f32_e32 v67, v84
	v_exp_f32_e32 v84, v85
	s_nop 0
	v_add_f32_e32 v85, v67, v84
	v_cvt_pk_bf16_f32 v180, v67, v84
	v_max_f32_e32 v67, v86, v87
	v_max3_f32 v67, v0, s86, v67
	v_exp_f32_e32 v84, v86
	v_exp_f32_e32 v0, v87
	s_nop 0
	v_pk_add_f32 v[86:87], v[84:85], v[0:1]
	s_nop 0
	v_pk_add_f32 v[86:87], v[86:87], v[86:87] op_sel_hi:[0,1]
	v_cvt_pk_bf16_f32 v181, v84, v0
	ds_read_b128 v[108:111], v241 offset:17408
	v_max_f32_e32 v0, v88, v89
	v_exp_f32_e32 v84, v88
	v_exp_f32_e32 v86, v89
	s_waitcnt lgkmcnt(4)
	v_mfma_f32_32x32x16_bf16 v[68:83], v[120:123], v[168:171], v[68:83]
	v_add_f32_e32 v85, v84, v86
	v_cvt_pk_bf16_f32 v182, v84, v86
	v_max_f32_e32 v84, v90, v91
	v_max3_f32 v0, v67, v0, v84
	v_exp_f32_e32 v84, v90
	v_exp_f32_e32 v86, v91
	s_nop 0
	v_pk_add_f32 v[88:89], v[84:85], v[86:87]
	s_nop 0
	v_pk_add_f32 v[88:89], v[88:89], v[88:89] op_sel_hi:[0,1]
	v_cvt_pk_bf16_f32 v183, v84, v86
	ds_read_b128 v[116:119], v241 offset:22016
	v_max_f32_e32 v67, v92, v93
	v_exp_f32_e32 v84, v92
	v_exp_f32_e32 v86, v93
	v_exp_f32_e32 v88, v95
	s_waitcnt lgkmcnt(3)
	v_mfma_f32_32x32x16_bf16 v[68:83], v[104:107], v[172:175], v[68:83]
	v_add_f32_e32 v85, v84, v86
	v_cvt_pk_bf16_f32 v184, v84, v86
	v_max_f32_e32 v84, v94, v95
	v_max3_f32 v0, v0, v67, v84
	v_exp_f32_e32 v84, v94
	s_nop 0
	v_pk_add_f32 v[86:87], v[84:85], v[88:89]
	s_nop 0
	v_pk_add_f32 v[86:87], v[86:87], v[86:87] op_sel_hi:[0,1]
	v_cvt_pk_bf16_f32 v185, v84, v88
	ds_read_b128 v[132:135], v241 offset:26624
	v_max_f32_e32 v67, v96, v97
	v_exp_f32_e32 v84, v96
	v_exp_f32_e32 v86, v97
	s_waitcnt lgkmcnt(3)
	v_mfma_f32_32x32x16_bf16 v[68:83], v[100:103], v[176:179], v[68:83]
	v_add_f32_e32 v85, v84, v86
	v_cvt_pk_bf16_f32 v186, v84, v86
	v_max_f32_e32 v84, v98, v99
	v_max3_f32 v0, v0, v67, v84
	v_exp_f32_e32 v84, v98
	v_exp_f32_e32 v86, v99
	s_nop 0
	v_pk_add_f32 v[88:89], v[84:85], v[86:87]
	s_nop 0
	v_pk_add_f32 v[120:121], v[88:89], v[88:89] op_sel_hi:[0,1]
	v_cvt_pk_bf16_f32 v187, v84, v86
	ds_read_b128 v[188:191], v241 offset:17440
	s_waitcnt lgkmcnt(3)
	v_mfma_f32_32x32x16_bf16 v[84:99], v[108:111], v[180:183], v[34:49]
	v_max_f32_e32 v67, v69, v69
	v_max_f32_e32 v100, v68, v68
	v_exp_f32_e32 v68, v68
	v_exp_f32_e32 v69, v69
	v_max_f32_e32 v67, v100, v67
	v_add_f32_e32 v123, v68, v69
	v_cvt_pk_bf16_f32 v68, v68, v69
	ds_read_b128 v[214:217], v241 offset:22048
	s_waitcnt lgkmcnt(3)
	v_mfma_f32_32x32x16_bf16 v[100:115], v[116:119], v[180:183], v[18:33]
	v_exp_f32_e32 v120, v70
	v_exp_f32_e32 v122, v71
	v_max_f32_e32 v69, v70, v71
	v_pk_add_f32 v[70:71], v[120:121], v[122:123]
	v_max3_f32 v0, v0, v67, v69
	v_pk_add_f32 v[248:249], v[70:71], v[70:71] op_sel_hi:[0,1]
	v_cvt_pk_bf16_f32 v69, v120, v122
	ds_read_b128 v[218:221], v241 offset:26656
	s_waitcnt lgkmcnt(3)
	v_mfma_f32_32x32x16_bf16 v[116:131], v[132:135], v[180:183], v[2:17]
	v_max_f32_e32 v67, v72, v73
	v_exp_f32_e32 v70, v72
	v_exp_f32_e32 v71, v73
	s_nop 0
	v_add_f32_e32 v73, v70, v71
	v_cvt_pk_bf16_f32 v70, v70, v71
	v_mfma_f32_32x32x16_bf16 v[132:147], v[244:247], v[180:183], v[50:65]
	v_max_f32_e32 v71, v74, v75
	v_exp_f32_e32 v72, v74
	v_exp_f32_e32 v248, v75
	v_max3_f32 v0, v0, v67, v71
	v_pk_add_f32 v[74:75], v[72:73], v[248:249]
	s_nop 0
	v_pk_add_f32 v[244:245], v[74:75], v[74:75] op_sel_hi:[0,1]
	v_cvt_pk_bf16_f32 v71, v72, v248
	ds_read_b128 v[72:75], v241 offset:31264
	s_waitcnt lgkmcnt(3)
	v_mfma_f32_32x32x16_bf16 v[84:99], v[188:191], v[184:187], v[84:99]
	v_max_f32_e32 v67, v77, v77
	v_max_f32_e32 v180, v76, v76
	v_exp_f32_e32 v76, v76
	v_exp_f32_e32 v77, v77
	v_max_f32_e32 v67, v180, v67
	v_add_f32_e32 v189, v76, v77
	v_cvt_pk_bf16_f32 v76, v76, v77
	ds_read_b128 v[180:183], v241 offset:17472
	s_waitcnt lgkmcnt(3)
	v_mfma_f32_32x32x16_bf16 v[100:115], v[214:217], v[184:187], v[100:115]
	v_max_f32_e32 v77, v78, v79
	v_exp_f32_e32 v188, v78
	v_exp_f32_e32 v244, v79
	v_max3_f32 v0, v0, v67, v77
	v_pk_add_f32 v[78:79], v[188:189], v[244:245]
	s_nop 0
	v_pk_add_f32 v[246:247], v[78:79], v[78:79] op_sel_hi:[0,1]
	v_cvt_pk_bf16_f32 v77, v188, v244
	ds_read_b128 v[188:191], v241 offset:22080
	s_waitcnt lgkmcnt(3)
	v_mfma_f32_32x32x16_bf16 v[116:131], v[218:221], v[184:187], v[116:131]
	v_max_f32_e32 v67, v80, v81
	v_exp_f32_e32 v78, v80
	v_exp_f32_e32 v79, v81
	s_nop 0
	v_add_f32_e32 v81, v78, v79
	v_cvt_pk_bf16_f32 v78, v78, v79
	ds_read_b128 v[214:217], v241 offset:26688
	s_waitcnt lgkmcnt(3)
	v_mfma_f32_32x32x16_bf16 v[132:147], v[72:75], v[184:187], v[132:147]
	v_exp_f32_e32 v80, v82
	v_exp_f32_e32 v246, v83
	v_max_f32_e32 v220, v82, v83
	v_pk_add_f32 v[218:219], v[80:81], v[246:247]
	v_cvt_pk_bf16_f32 v79, v80, v246
	ds_read_b128 v[72:75], v241 offset:31296
	ds_read_b128 v[80:83], v241 offset:17504
	s_waitcnt lgkmcnt(4)
	v_mfma_f32_32x32x16_bf16 v[84:99], v[180:183], v[68:71], v[84:99]
	ds_read_b128 v[180:183], v241 offset:22112
	s_waitcnt lgkmcnt(4)
	v_mfma_f32_32x32x16_bf16 v[100:115], v[188:191], v[68:71], v[100:115]
	ds_read_b128 v[184:187], v241 offset:26720
	s_waitcnt lgkmcnt(4)
	v_mfma_f32_32x32x16_bf16 v[116:131], v[214:217], v[68:71], v[116:131]
	s_waitcnt lgkmcnt(3)
	v_mfma_f32_32x32x16_bf16 v[132:147], v[72:75], v[68:71], v[132:147]
	ds_read_b128 v[68:71], v241 offset:31328
	s_waitcnt lgkmcnt(3)
	v_mfma_f32_32x32x16_bf16 v[84:99], v[80:83], v[76:79], v[84:99]
	s_waitcnt lgkmcnt(2)
	v_mfma_f32_32x32x16_bf16 v[100:115], v[180:183], v[76:79], v[100:115]
	s_waitcnt lgkmcnt(1)
	v_mfma_f32_32x32x16_bf16 v[116:131], v[184:187], v[76:79], v[116:131]
	s_waitcnt lgkmcnt(0)
	v_mfma_f32_32x32x16_bf16 v[132:147], v[68:71], v[76:79], v[132:147]
	v_max3_f32 v67, v0, v67, v220
	ds_bpermute_b32 v68, v195, v67
	v_add_f32_e32 v0, v218, v219
	v_add_f32_e32 v0, v240, v0
	s_waitcnt lgkmcnt(0)
	v_max_f32_e32 v68, v68, v68
	v_max_f32_e32 v67, v67, v68
	v_cmp_lt_f32_e32 vcc, s87, v67
	s_cmp_lg_u64 vcc, 0
	s_cselect_b64 s[0:1], -1, 0
	s_cbranch_execz .LBB0_96
	s_branch .LBB0_97

.LBB0_107:
	s_add_i32 s70, s70, s59
	s_ashr_i32 s1, s70, 31
	v_mov_b32_e32 v8, v222
	s_add_u32 s0, s70, s24
	s_addc_u32 s1, s1, s25
	v_and_b32_e32 v0, 31, v8
	v_lshl_add_u64 v[166:167], s[0:1], 0, v[0:1]
	v_readlane_b32 s0, v251, 61
	v_readlane_b32 s1, v251, 62
	s_movk_i32 s73, 0x600
	v_ashrrev_i32_e32 v180, 5, v8
	v_mov_b64_e32 v[2:3], s[0:1]
	v_mad_u64_u32 v[2:3], s[0:1], v166, s73, v[2:3]
	s_mul_i32 s0, s68, 0xc0
	s_ashr_i32 s1, s0, 31
	v_mad_i32_i24 v3, v167, s73, v3
	s_lshl_b64 s[28:29], s[0:1], 1
	v_lshlrev_b32_e32 v4, 3, v180
	v_lshl_add_u64 v[2:3], v[2:3], 0, s[28:29]
	v_ashrrev_i32_e32 v5, 31, v4
	v_lshl_add_u64 v[2:3], v[4:5], 1, v[2:3]
	v_mov_b32_e32 v42, v223
	s_mov_b32 s40, 0x2aaaaaab
	global_load_dwordx4 v[98:101], v[2:3], off
	global_load_dwordx4 v[102:105], v[2:3], off offset:32
	global_load_dwordx4 v[106:109], v[2:3], off offset:64
	global_load_dwordx4 v[110:113], v[2:3], off offset:96
	global_load_dwordx4 v[114:117], v[2:3], off offset:128
	global_load_dwordx4 v[118:121], v[2:3], off offset:160
	global_load_dwordx4 v[122:125], v[2:3], off offset:192
	global_load_dwordx4 v[126:129], v[2:3], off offset:224
	global_load_dwordx4 v[130:133], v[2:3], off offset:256
	global_load_dwordx4 v[134:137], v[2:3], off offset:288
	global_load_dwordx4 v[138:141], v[2:3], off offset:320
	global_load_dwordx4 v[142:145], v[2:3], off offset:352
	v_mul_hi_i32 v2, v42, s40
	v_lshrrev_b32_e32 v3, 31, v2
	v_ashrrev_i32_e32 v2, 2, v2
	v_add_u32_e32 v41, v2, v3
	v_mul_lo_u32 v2, v41, 24
	v_add_u32_e32 v13, 0x200, v42
	v_sub_u32_e32 v12, v42, v2
	v_mul_hi_i32 v2, v13, s40
	v_lshrrev_b32_e32 v3, 31, v2
	v_ashrrev_i32_e32 v2, 2, v2
	v_add_u32_e32 v40, v2, v3
	v_mul_lo_u32 v2, v40, 24
	s_mul_i32 s72, s24, 0x600
	v_readlane_b32 s0, v251, 63
	v_lshlrev_b32_e32 v4, 1, v8
	v_sub_u32_e32 v14, v13, v2
	v_add_u32_e32 v2, 0x400, v42
	s_mul_hi_i32 s70, s24, 0x600
	v_readlane_b32 s1, v252, 0
	s_add_u32 s0, s0, s72
	v_and_b32_e32 v9, 8, v4
	v_lshrrev_b32_e32 v4, 1, v8
	v_mul_hi_i32 v3, v2, s40
	s_addc_u32 s1, s1, s70
	v_and_b32_e32 v10, 4, v4
	v_lshrrev_b32_e32 v4, 31, v3
	v_ashrrev_i32_e32 v3, 2, v3
	s_add_u32 s34, s0, s28
	v_add_u32_e32 v43, v3, v4
	s_addc_u32 s35, s1, s29
	v_mul_lo_u32 v3, v43, 24
	v_lshlrev_b32_e32 v6, 3, v12
	v_sub_u32_e32 v15, v2, v3
	v_mov_b64_e32 v[2:3], s[34:35]
	v_ashrrev_i32_e32 v7, 31, v6
	v_mad_i64_i32 v[4:5], s[34:35], v41, s73, v[2:3]
	v_lshlrev_b64 v[34:35], 1, v[6:7]
	v_lshlrev_b32_e32 v6, 3, v14
	v_lshl_add_u64 v[4:5], v[4:5], 0, v[34:35]
	v_ashrrev_i32_e32 v7, 31, v6
	global_load_dwordx4 v[146:149], v[4:5], off
	v_mad_i64_i32 v[4:5], s[34:35], v40, s73, v[2:3]
	v_lshlrev_b64 v[36:37], 1, v[6:7]
	v_lshl_add_u64 v[4:5], v[4:5], 0, v[36:37]
	s_lshl_b32 s0, s68, 7
	global_load_dwordx4 v[150:153], v[4:5], off
	v_lshlrev_b32_e32 v4, 3, v15
	s_ashr_i32 s1, s0, 31
	v_readlane_b32 s30, v252, 1
	v_ashrrev_i32_e32 v5, 31, v4
	s_mul_hi_i32 s27, s0, 0xc000
	v_readlane_b32 s31, v252, 2
	s_add_u32 s30, s30, s26
	v_mad_i64_i32 v[2:3], s[34:35], v43, s73, v[2:3]
	v_lshlrev_b64 v[38:39], 1, v[4:5]
	s_addc_u32 s31, s31, s27
	s_lshl_b64 s[24:25], s[24:25], 1
	v_lshl_add_u64 v[2:3], v[2:3], 0, v[38:39]
	s_add_u32 s30, s30, s24
	global_load_dwordx4 v[154:157], v[2:3], off
	v_lshlrev_b32_e32 v2, 4, v42
	s_addc_u32 s31, s31, s25
	v_and_b32_e32 v168, 0x70, v2
	v_mov_b32_e32 v169, v1
	v_lshl_add_u64 v[2:3], s[30:31], 0, v[168:169]
	v_ashrrev_i32_e32 v44, 3, v42
	v_mad_i64_i32 v[4:5], s[30:31], v44, s85, v[2:3]
	v_ashrrev_i32_e32 v45, 3, v13
	global_load_dwordx4 v[158:161], v[4:5], off
	v_mad_i64_i32 v[2:3], s[30:31], v45, s85, v[2:3]
	global_load_dwordx4 v[162:165], v[2:3], off
	s_movk_i32 s31, 0x190
	v_mul_lo_u32 v169, v41, s31
	v_lshlrev_b32_e32 v181, 4, v12
	v_add3_u32 v2, 0, v169, v181
	v_mul_lo_u32 v182, v40, s31
	v_lshlrev_b32_e32 v183, 4, v14
	v_mul_lo_u32 v184, v43, s31
	v_lshlrev_b32_e32 v185, 4, v15
	s_movk_i32 s30, 0x90
	v_mul_lo_u32 v186, v44, s30
	v_mul_lo_u32 v187, v45, s30
	v_and_b32_e32 v11, 19, v8
	v_mul_u32_u24_e32 v190, 0x90, v0
	s_mov_b64 s[34:35], 0x26900080
	s_mov_b32 s40, 0
	s_mov_b32 s41, s40
	s_mov_b32 s42, s40
	s_mov_b32 s43, s40
	s_mov_b32 s44, s40
	s_mov_b32 s45, s40
	s_mov_b32 s46, s40
	s_mov_b32 s47, s40
	s_mov_b32 s48, s40
	s_mov_b32 s49, s40
	s_mov_b32 s50, s40
	s_mov_b32 s51, s40
	s_mov_b32 s52, s40
	s_mov_b32 s53, s40
	s_mov_b32 s54, s40
	s_mov_b32 s55, s40
	s_mov_b32 s30, 64
	v_mov_b32_e32 v193, 0
	s_waitcnt vmcnt(0)
	ds_write_b128 v2, v[146:149]
	v_add3_u32 v2, 0, v182, v183
	s_waitcnt vmcnt(3)
	ds_write_b128 v2, v[150:153]
	v_add3_u32 v2, 0, v184, v185
	s_waitcnt vmcnt(2)
	ds_write_b128 v2, v[154:157]
	v_add_u32_e32 v2, 0, v168
	v_add_u32_e32 v3, v2, v186
	v_add_u32_e32 v2, v2, v187
	s_waitcnt vmcnt(1)
	ds_write_b128 v3, v[158:161] offset:25600
	v_ashrrev_i32_e32 v3, 1, v8
	v_and_b32_e32 v188, -16, v3
	s_waitcnt vmcnt(0)
	ds_write_b128 v2, v[162:165] offset:25600
	v_or3_b32 v2, v11, v9, v10
	v_mad_u32_u24 v189, v2, s31, v188
	v_add_u32_e32 v0, 0, v189
	s_waitcnt lgkmcnt(0)
	s_barrier
	ds_read_b128 v[18:21], v0
	ds_read_b128 v[46:49], v0 offset:32
	s_waitcnt lgkmcnt(1)
	v_mfma_f32_32x32x16_bf16 v[18:33], v[18:21], v[98:101], 0
	s_mov_b32 s31, 0xc2700000
	v_mov_b64_e32 v[2:3], s[40:41]
	v_mov_b64_e32 v[16:17], s[54:55]
	v_mov_b64_e32 v[4:5], s[42:43]
	v_mov_b64_e32 v[6:7], s[44:45]
	v_mov_b64_e32 v[8:9], s[46:47]
	v_mov_b64_e32 v[10:11], s[48:49]
	s_waitcnt lgkmcnt(0)
	v_mfma_f32_32x32x16_bf16 v[18:33], v[46:49], v[102:105], v[18:33]
	ds_read_b128 v[46:49], v0 offset:64
	v_mov_b64_e32 v[12:13], s[50:51]
	v_mov_b64_e32 v[14:15], s[52:53]
	v_mov_b64_e32 v[64:65], v[16:17]
	v_mov_b64_e32 v[62:63], v[14:15]
	v_mov_b64_e32 v[60:61], v[12:13]
	v_mov_b64_e32 v[58:59], v[10:11]
	s_waitcnt lgkmcnt(0)
	v_mfma_f32_32x32x16_bf16 v[18:33], v[46:49], v[106:109], v[18:33]
	ds_read_b128 v[46:49], v0 offset:96
	v_mov_b64_e32 v[56:57], v[8:9]
	v_mov_b64_e32 v[54:55], v[6:7]
	v_mov_b64_e32 v[52:53], v[4:5]
	v_mov_b64_e32 v[50:51], v[2:3]
	s_waitcnt lgkmcnt(0)
	v_mfma_f32_32x32x16_bf16 v[18:33], v[46:49], v[110:113], v[18:33]
	ds_read_b128 v[46:49], v0 offset:128
	s_waitcnt lgkmcnt(0)
	v_mfma_f32_32x32x16_bf16 v[18:33], v[46:49], v[114:117], v[18:33]
	ds_read_b128 v[46:49], v0 offset:160
	s_waitcnt lgkmcnt(0)
	v_mfma_f32_32x32x16_bf16 v[18:33], v[46:49], v[118:121], v[18:33]
	ds_read_b128 v[46:49], v0 offset:192
	s_waitcnt lgkmcnt(0)
	v_mfma_f32_32x32x16_bf16 v[18:33], v[46:49], v[122:125], v[18:33]
	ds_read_b128 v[46:49], v0 offset:224
	s_waitcnt lgkmcnt(0)
	v_mfma_f32_32x32x16_bf16 v[18:33], v[46:49], v[126:129], v[18:33]
	ds_read_b128 v[46:49], v0 offset:256
	s_waitcnt lgkmcnt(0)
	v_mfma_f32_32x32x16_bf16 v[18:33], v[46:49], v[130:133], v[18:33]
	ds_read_b128 v[46:49], v0 offset:288
	s_waitcnt lgkmcnt(0)
	v_mfma_f32_32x32x16_bf16 v[18:33], v[46:49], v[134:137], v[18:33]
	ds_read_b128 v[46:49], v0 offset:320
	s_waitcnt lgkmcnt(0)
	v_mfma_f32_32x32x16_bf16 v[18:33], v[46:49], v[138:141], v[18:33]
	ds_read_b128 v[46:49], v0 offset:352
	s_waitcnt lgkmcnt(0)
	v_mfma_f32_32x32x16_bf16 v[18:33], v[46:49], v[142:145], v[18:33]
	s_nop 11
	v_max_f32_e32 v0, v18, v19
	v_max3_f32 v0, v0, v20, v21
	v_max3_f32 v0, v0, v22, v23
	v_max3_f32 v0, v0, v24, v25
	v_and_b32_e32 v19, 64, v210
	v_max3_f32 v0, v0, v26, v27
	v_xor_b32_e32 v18, 32, v210
	v_add_u32_e32 v19, 64, v19
	v_max3_f32 v0, v0, v28, v29
	v_cmp_lt_i32_e32 vcc, v18, v19
	v_max3_f32 v0, v0, v30, v31
	v_max3_f32 v0, v0, v32, v33
	v_cndmask_b32_e32 v18, v210, v18, vcc
	v_lshlrev_b32_e32 v191, 2, v18
	ds_bpermute_b32 v18, v191, v0
	s_waitcnt lgkmcnt(0)
	v_max3_f32 v192, v0, v18, s31
	v_mov_b64_e32 v[18:19], s[26:27]
	v_and_b32_e32 v0, 7, v42
	v_mad_i64_i32 v[20:21], s[26:27], v45, s85, v[18:19]
	v_lshlrev_b32_e32 v0, 4, v0
	v_mad_i64_i32 v[18:19], s[26:27], v44, s85, v[18:19]
	v_lshl_add_u64 v[20:21], v[20:21], 0, v[0:1]
	v_lshl_add_u64 v[18:19], v[18:19], 0, v[0:1]
	v_lshl_add_u64 v[20:21], v[20:21], 0, s[24:25]
	v_lshl_add_u64 v[18:19], v[18:19], 0, s[24:25]
	s_add_u32 s24, s28, s72
	s_addc_u32 s25, s29, s70
	v_lshl_add_u64 v[172:173], v[18:19], 0, s[34:35]
	v_mov_b64_e32 v[18:19], s[24:25]
	v_lshl_add_u64 v[170:171], v[20:21], 0, s[34:35]
	v_mad_i64_i32 v[20:21], s[24:25], v41, s73, v[18:19]
	v_lshl_add_u64 v[20:21], v[20:21], 0, v[34:35]
	s_mov_b64 s[26:27], 0x24518000
	v_lshl_add_u64 v[174:175], v[20:21], 0, s[26:27]
	v_mad_i64_i32 v[20:21], s[24:25], v40, s73, v[18:19]
	v_mad_i64_i32 v[18:19], s[24:25], v43, s73, v[18:19]
	v_lshl_add_u64 v[20:21], v[20:21], 0, v[36:37]
	v_lshl_add_u64 v[18:19], v[18:19], 0, v[38:39]
	v_lshl_add_u64 v[176:177], v[20:21], 0, s[26:27]
	v_lshl_add_u64 v[178:179], v[18:19], 0, s[26:27]
	v_mov_b64_e32 v[48:49], v[16:17]
	v_mov_b64_e32 v[32:33], v[16:17]
	v_mov_b64_e32 v[46:47], v[14:15]
	v_mov_b64_e32 v[44:45], v[12:13]
	v_mov_b64_e32 v[42:43], v[10:11]
	v_mov_b64_e32 v[40:41], v[8:9]
	v_mov_b64_e32 v[38:39], v[6:7]
	v_mov_b64_e32 v[36:37], v[4:5]
	v_mov_b64_e32 v[34:35], v[2:3]
	v_mov_b64_e32 v[30:31], v[14:15]
	v_mov_b64_e32 v[28:29], v[12:13]
	v_mov_b64_e32 v[26:27], v[10:11]
	v_mov_b64_e32 v[24:25], v[8:9]
	v_mov_b64_e32 v[22:23], v[6:7]
	v_mov_b64_e32 v[20:21], v[4:5]
	v_mov_b64_e32 v[18:19], v[2:3]
	s_mov_b64 s[34:35], 0x18000
	s_branch .LBB0_109

.LBB0_111:
	s_mul_i32 s28, s40, 0xac00
	s_add_i32 s28, s28, 0
	v_add_u32_e32 v220, s28, v189
	ds_read_b128 v[194:197], v220
	ds_read_b128 v[198:201], v220 offset:32
	ds_read_b128 v[202:205], v220 offset:64
	v_xor_b32_e32 v66, 0x80000000, v192
	v_mov_b32_e32 v67, v66
	v_mov_b32_e32 v68, v66
	v_mov_b32_e32 v69, v66
	v_mov_b32_e32 v70, v66
	v_mov_b32_e32 v71, v66
	v_mov_b32_e32 v72, v66
	v_mov_b32_e32 v73, v66
	v_mov_b32_e32 v74, v66
	v_mov_b32_e32 v75, v66
	v_mov_b32_e32 v76, v66
	v_mov_b32_e32 v77, v66
	v_mov_b32_e32 v78, v66
	v_mov_b32_e32 v79, v66
	v_mov_b32_e32 v80, v66
	v_mov_b32_e32 v81, v66
	s_waitcnt lgkmcnt(2)
	s_nop 0
	v_mfma_f32_32x32x16_bf16 v[82:97], v[194:197], v[98:101], v[66:81]
	ds_read_b128 v[194:197], v220 offset:96
	s_waitcnt lgkmcnt(2)
	v_mfma_f32_32x32x16_bf16 v[82:97], v[198:201], v[102:105], v[82:97]
	ds_read_b128 v[198:201], v220 offset:128
	s_waitcnt lgkmcnt(2)
	v_mfma_f32_32x32x16_bf16 v[82:97], v[202:205], v[106:109], v[82:97]
	ds_read_b128 v[202:205], v220 offset:160
	s_waitcnt lgkmcnt(2)
	v_mfma_f32_32x32x16_bf16 v[82:97], v[194:197], v[110:113], v[82:97]
	ds_read_b128 v[194:197], v220 offset:192
	s_waitcnt lgkmcnt(2)
	v_mfma_f32_32x32x16_bf16 v[82:97], v[198:201], v[114:117], v[82:97]
	ds_read_b128 v[198:201], v220 offset:224
	s_waitcnt lgkmcnt(2)
	v_mfma_f32_32x32x16_bf16 v[82:97], v[202:205], v[118:121], v[82:97]
	ds_read_b128 v[202:205], v220 offset:256
	s_waitcnt lgkmcnt(2)
	v_mfma_f32_32x32x16_bf16 v[82:97], v[194:197], v[122:125], v[82:97]
	ds_read_b128 v[194:197], v220 offset:288
	s_waitcnt lgkmcnt(2)
	v_mfma_f32_32x32x16_bf16 v[82:97], v[198:201], v[126:129], v[82:97]
	ds_read_b128 v[198:201], v220 offset:320
	s_waitcnt lgkmcnt(2)
	v_mfma_f32_32x32x16_bf16 v[82:97], v[202:205], v[130:133], v[82:97]
	ds_read_b128 v[202:205], v220 offset:352
	s_waitcnt lgkmcnt(2)
	v_mfma_f32_32x32x16_bf16 v[82:97], v[194:197], v[134:137], v[82:97]
	ds_read_b128 v[194:197], v220 offset:12800
	s_waitcnt lgkmcnt(2)
	v_mfma_f32_32x32x16_bf16 v[82:97], v[198:201], v[138:141], v[82:97]
	ds_read_b128 v[198:201], v220 offset:12832
	s_waitcnt lgkmcnt(2)
	v_mfma_f32_32x32x16_bf16 v[82:97], v[202:205], v[142:145], v[82:97]
	ds_read_b128 v[202:205], v220 offset:12864
	v_add3_u32 v221, s28, v190, v188
	s_waitcnt lgkmcnt(2)
	v_mfma_f32_32x32x16_bf16 v[66:81], v[194:197], v[98:101], v[66:81]
	ds_read_b128 v[194:197], v220 offset:12896
	ds_read_b128 v[214:217], v220 offset:12928
	s_waitcnt lgkmcnt(3)
	v_mfma_f32_32x32x16_bf16 v[66:81], v[198:201], v[102:105], v[66:81]
	s_nop 3
	v_exp_f32_e32 v0, v82
	v_exp_f32_e32 v198, v83
	v_max_f32_e32 v83, v82, v83
	v_add_f32_e32 v219, v0, v198
	v_cvt_pk_bf16_f32 v82, v0, v198
	s_waitcnt lgkmcnt(2)
	v_mfma_f32_32x32x16_bf16 v[66:81], v[202:205], v[106:109], v[66:81]
	ds_read_b128 v[198:201], v220 offset:12960
	v_exp_f32_e32 v218, v84
	v_exp_f32_e32 v0, v85
	v_max_f32_e32 v84, v84, v85
	v_max3_f32 v226, v83, s86, v84
	v_pk_add_f32 v[84:85], v[218:219], v[0:1]
	v_cvt_pk_bf16_f32 v83, v218, v0
	v_pk_add_f32 v[218:219], v[84:85], v[84:85] op_sel_hi:[0,1]
	s_waitcnt lgkmcnt(2)
	v_mfma_f32_32x32x16_bf16 v[66:81], v[194:197], v[110:113], v[66:81]
	ds_read_b128 v[194:197], v220 offset:12992
	ds_read_b128 v[202:205], v220 offset:13024
	s_waitcnt lgkmcnt(3)
	v_mfma_f32_32x32x16_bf16 v[66:81], v[214:217], v[114:117], v[66:81]
	v_exp_f32_e32 v0, v86
	v_exp_f32_e32 v84, v87
	v_max_f32_e32 v85, v86, v87
	v_add_f32_e32 v87, v0, v84
	v_cvt_pk_bf16_f32 v84, v0, v84
	s_waitcnt lgkmcnt(2)
	v_mfma_f32_32x32x16_bf16 v[66:81], v[198:201], v[118:121], v[66:81]
	ds_read_b128 v[214:217], v220 offset:13056
	v_exp_f32_e32 v86, v88
	v_exp_f32_e32 v218, v89
	v_max_f32_e32 v0, v88, v89
	v_pk_add_f32 v[88:89], v[86:87], v[218:219]
	v_max3_f32 v0, v226, v85, v0
	v_cvt_pk_bf16_f32 v85, v86, v218
	v_pk_add_f32 v[218:219], v[88:89], v[88:89] op_sel_hi:[0,1]
	s_waitcnt lgkmcnt(2)
	v_mfma_f32_32x32x16_bf16 v[66:81], v[194:197], v[122:125], v[66:81]
	ds_read_b128 v[86:89], v220 offset:13088
	ds_read_b128 v[194:197], v220 offset:13120
	s_waitcnt lgkmcnt(3)
	v_mfma_f32_32x32x16_bf16 v[66:81], v[202:205], v[126:129], v[66:81]
	v_exp_f32_e32 v198, v90
	v_exp_f32_e32 v199, v91
	v_max_f32_e32 v91, v90, v91
	v_add_f32_e32 v203, v198, v199
	v_cvt_pk_bf16_f32 v90, v198, v199
	s_waitcnt lgkmcnt(2)
	v_mfma_f32_32x32x16_bf16 v[66:81], v[214:217], v[130:133], v[66:81]
	ds_read_b128 v[198:201], v220 offset:13152
	v_exp_f32_e32 v202, v92
	v_exp_f32_e32 v218, v93
	v_max_f32_e32 v92, v92, v93
	v_max3_f32 v0, v0, v91, v92
	v_pk_add_f32 v[92:93], v[202:203], v[218:219]
	v_cvt_pk_bf16_f32 v91, v202, v218
	v_pk_add_f32 v[214:215], v[92:93], v[92:93] op_sel_hi:[0,1]
	s_waitcnt lgkmcnt(2)
	v_mfma_f32_32x32x16_bf16 v[66:81], v[86:89], v[134:137], v[66:81]
	ds_read_b128 v[86:89], v221 offset:25600
	ds_read_b128 v[202:205], v221 offset:30208
	s_waitcnt lgkmcnt(3)
	v_mfma_f32_32x32x16_bf16 v[66:81], v[194:197], v[138:141], v[66:81]
	v_exp_f32_e32 v92, v94
	v_exp_f32_e32 v93, v95
	v_max_f32_e32 v216, v94, v95
	v_add_f32_e32 v95, v92, v93
	v_cvt_pk_bf16_f32 v92, v92, v93
	ds_read_b128 v[194:197], v221 offset:34816
	s_waitcnt lgkmcnt(3)
	v_mfma_f32_32x32x16_bf16 v[66:81], v[198:201], v[142:145], v[66:81]
	v_exp_f32_e32 v94, v96
	v_exp_f32_e32 v214, v97
	v_max_f32_e32 v93, v96, v97
	v_pk_add_f32 v[96:97], v[94:95], v[214:215]
	v_max3_f32 v0, v0, v216, v93
	v_cvt_pk_bf16_f32 v93, v94, v214
	v_pk_add_f32 v[214:215], v[96:97], v[96:97] op_sel_hi:[0,1]
	ds_read_b128 v[94:97], v221 offset:39424
	ds_read_b128 v[198:201], v221 offset:25632
	s_waitcnt lgkmcnt(4)
	v_mfma_f32_32x32x16_bf16 v[2:17], v[86:89], v[82:85], v[2:17]
	s_nop 0
	v_exp_f32_e32 v86, v66
	v_exp_f32_e32 v87, v67
	v_max_f32_e32 v67, v66, v67
	v_add_f32_e32 v217, v86, v87
	v_cvt_pk_bf16_f32 v66, v86, v87
	ds_read_b128 v[86:89], v221 offset:30240
	s_waitcnt lgkmcnt(4)
	v_mfma_f32_32x32x16_bf16 v[50:65], v[202:205], v[82:85], v[50:65]
	v_exp_f32_e32 v214, v68
	v_exp_f32_e32 v216, v69
	v_max_f32_e32 v68, v68, v69
	v_max3_f32 v0, v0, v67, v68
	v_pk_add_f32 v[68:69], v[214:215], v[216:217]
	v_cvt_pk_bf16_f32 v67, v214, v216
	v_pk_add_f32 v[218:219], v[68:69], v[68:69] op_sel_hi:[0,1]
	ds_read_b128 v[202:205], v221 offset:34848
	s_waitcnt lgkmcnt(4)
	v_mfma_f32_32x32x16_bf16 v[34:49], v[194:197], v[82:85], v[34:49]
	v_exp_f32_e32 v68, v70
	v_exp_f32_e32 v69, v71
	v_max_f32_e32 v214, v70, v71
	v_add_f32_e32 v71, v68, v69
	v_cvt_pk_bf16_f32 v68, v68, v69
	ds_read_b128 v[194:197], v221 offset:39456
	s_waitcnt lgkmcnt(4)
	v_mfma_f32_32x32x16_bf16 v[18:33], v[94:97], v[82:85], v[18:33]
	v_exp_f32_e32 v70, v72
	v_exp_f32_e32 v218, v73
	v_max_f32_e32 v69, v72, v73
	v_pk_add_f32 v[72:73], v[70:71], v[218:219]
	v_max3_f32 v0, v0, v214, v69
	v_pk_add_f32 v[72:73], v[72:73], v[72:73] op_sel_hi:[0,1]
	v_cvt_pk_bf16_f32 v69, v70, v218
	s_waitcnt lgkmcnt(3)
	v_mfma_f32_32x32x16_bf16 v[2:17], v[198:201], v[90:93], v[2:17]
	v_exp_f32_e32 v70, v74
	v_exp_f32_e32 v71, v75
	v_max_f32_e32 v94, v74, v75
	v_add_f32_e32 v75, v70, v71
	v_cvt_pk_bf16_f32 v70, v70, v71
	v_exp_f32_e32 v74, v76
	v_exp_f32_e32 v72, v77
	v_max_f32_e32 v71, v76, v77
	v_pk_add_f32 v[76:77], v[74:75], v[72:73]
	v_max3_f32 v0, v0, v94, v71
	v_pk_add_f32 v[94:95], v[76:77], v[76:77] op_sel_hi:[0,1]
	v_cvt_pk_bf16_f32 v71, v74, v72
	ds_read_b128 v[74:77], v221 offset:30272
	s_waitcnt lgkmcnt(3)
	v_mfma_f32_32x32x16_bf16 v[50:65], v[86:89], v[90:93], v[50:65]
	ds_read_b128 v[82:85], v221 offset:25664
	ds_read_b128 v[86:89], v221 offset:34880
	s_waitcnt lgkmcnt(4)
	v_mfma_f32_32x32x16_bf16 v[34:49], v[202:205], v[90:93], v[34:49]
	v_exp_f32_e32 v72, v78
	v_exp_f32_e32 v73, v79
	v_max_f32_e32 v198, v78, v79
	v_add_f32_e32 v79, v72, v73
	v_cvt_pk_bf16_f32 v72, v72, v73
	s_waitcnt lgkmcnt(2)
	v_mfma_f32_32x32x16_bf16 v[50:65], v[74:77], v[66:69], v[50:65]
	ds_read_b128 v[74:77], v221 offset:34912
	v_mfma_f32_32x32x16_bf16 v[18:33], v[194:197], v[90:93], v[18:33]
	v_exp_f32_e32 v78, v80
	v_exp_f32_e32 v94, v81
	v_max_f32_e32 v194, v80, v81
	v_pk_add_f32 v[96:97], v[78:79], v[94:95]
	v_cvt_pk_bf16_f32 v73, v78, v94
	ds_read_b128 v[78:81], v221 offset:25696
	s_waitcnt lgkmcnt(3)
	v_mfma_f32_32x32x16_bf16 v[2:17], v[82:85], v[66:69], v[2:17]
	ds_read_b128 v[82:85], v221 offset:39488
	ds_read_b128 v[90:93], v221 offset:30304
	s_waitcnt lgkmcnt(4)
	v_mfma_f32_32x32x16_bf16 v[34:49], v[86:89], v[66:69], v[34:49]
	ds_read_b128 v[86:89], v221 offset:39520
	s_waitcnt lgkmcnt(2)
	v_mfma_f32_32x32x16_bf16 v[18:33], v[82:85], v[66:69], v[18:33]
	v_mfma_f32_32x32x16_bf16 v[2:17], v[78:81], v[70:73], v[2:17]
	s_waitcnt lgkmcnt(1)
	v_mfma_f32_32x32x16_bf16 v[50:65], v[90:93], v[70:73], v[50:65]
	v_mfma_f32_32x32x16_bf16 v[34:49], v[74:77], v[70:73], v[34:49]
	s_waitcnt lgkmcnt(0)
	v_mfma_f32_32x32x16_bf16 v[18:33], v[86:89], v[70:73], v[18:33]
	v_max3_f32 v0, v0, v198, v194
	ds_bpermute_b32 v66, v191, v0
	v_add_f32_e32 v67, v96, v97
	v_add_f32_e32 v193, v193, v67
	s_waitcnt lgkmcnt(0)
	v_max_f32_e32 v66, v66, v66
	v_max_f32_e32 v0, v0, v66
	v_cmp_lt_f32_e32 vcc, s87, v0
	s_cbranch_vccz .LBB0_113
	v_max_f32_e32 v0, v0, v0
	v_max_f32_e32 v66, 0, v0
	v_exp_f32_e64 v0, -v66
	v_add_f32_e32 v192, v192, v66
	v_mul_f32_e32 v193, v193, v0
	v_pk_mul_f32 v[16:17], v[16:17], v[0:1] op_sel_hi:[1,0]
	v_pk_mul_f32 v[14:15], v[14:15], v[0:1] op_sel_hi:[1,0]
	v_pk_mul_f32 v[12:13], v[12:13], v[0:1] op_sel_hi:[1,0]
	v_pk_mul_f32 v[10:11], v[10:11], v[0:1] op_sel_hi:[1,0]
	v_pk_mul_f32 v[8:9], v[8:9], v[0:1] op_sel_hi:[1,0]
	v_pk_mul_f32 v[6:7], v[6:7], v[0:1] op_sel_hi:[1,0]
	v_pk_mul_f32 v[4:5], v[4:5], v[0:1] op_sel_hi:[1,0]
	v_pk_mul_f32 v[2:3], v[2:3], v[0:1] op_sel_hi:[1,0]
	v_pk_mul_f32 v[64:65], v[64:65], v[0:1] op_sel_hi:[1,0]
	v_pk_mul_f32 v[62:63], v[62:63], v[0:1] op_sel_hi:[1,0]
	v_pk_mul_f32 v[60:61], v[60:61], v[0:1] op_sel_hi:[1,0]
	v_pk_mul_f32 v[58:59], v[58:59], v[0:1] op_sel_hi:[1,0]
	v_pk_mul_f32 v[56:57], v[56:57], v[0:1] op_sel_hi:[1,0]
	v_pk_mul_f32 v[54:55], v[54:55], v[0:1] op_sel_hi:[1,0]
	v_pk_mul_f32 v[52:53], v[52:53], v[0:1] op_sel_hi:[1,0]
	v_pk_mul_f32 v[50:51], v[50:51], v[0:1] op_sel_hi:[1,0]
	v_pk_mul_f32 v[48:49], v[48:49], v[0:1] op_sel_hi:[1,0]
	v_pk_mul_f32 v[46:47], v[46:47], v[0:1] op_sel_hi:[1,0]
	v_pk_mul_f32 v[44:45], v[44:45], v[0:1] op_sel_hi:[1,0]
	v_pk_mul_f32 v[42:43], v[42:43], v[0:1] op_sel_hi:[1,0]
	v_pk_mul_f32 v[40:41], v[40:41], v[0:1] op_sel_hi:[1,0]
	v_pk_mul_f32 v[38:39], v[38:39], v[0:1] op_sel_hi:[1,0]
	v_pk_mul_f32 v[36:37], v[36:37], v[0:1] op_sel_hi:[1,0]
	v_pk_mul_f32 v[34:35], v[34:35], v[0:1] op_sel_hi:[1,0]
	v_pk_mul_f32 v[32:33], v[32:33], v[0:1] op_sel_hi:[1,0]
	v_pk_mul_f32 v[30:31], v[30:31], v[0:1] op_sel_hi:[1,0]
	v_pk_mul_f32 v[28:29], v[28:29], v[0:1] op_sel_hi:[1,0]
	v_pk_mul_f32 v[26:27], v[26:27], v[0:1] op_sel_hi:[1,0]
	v_pk_mul_f32 v[24:25], v[24:25], v[0:1] op_sel_hi:[1,0]
	v_pk_mul_f32 v[22:23], v[22:23], v[0:1] op_sel_hi:[1,0]
	v_pk_mul_f32 v[20:21], v[20:21], v[0:1] op_sel_hi:[1,0]
	v_pk_mul_f32 v[18:19], v[18:19], v[0:1] op_sel_hi:[1,0]
